# instruction selection: accumulator zeroing between GEMM units uses v_mov_b64 of even-aligned pairs instead of two v_mov_b32 (6 unit loops, 378 fewer VALU per pass)
# speedup vs baseline: 1.0037x; 1.0020x over previous
; template <class Epi, bool SP2, class Sched>
; __device__ __forceinline__ void gemm_phase(LAS unsigned char* lds, const Gemm g, const Sched& S, const Epi& E) {
;     ...
;         const bool has_next = S.next(ui + 1, nxt);
;         const char* nA = has_next ? (const char*)g.A + (size_t)nxt.pm * tstep + nxt.ko : cA; const char* nB = has_next ? (const char*)g.Bt + (size_t)nxt.pn * tstepB + nxt.ko : cB;
;     ...
; #pragma unroll
;         for (int a = 0; a < 2; ++a)
; #pragma unroll
;             for (int b = 0; b < 2; ++b)
; #pragma unroll
;                 for (int m = 0; m < 4; ++m)
; #pragma unroll
;                     for (int n = 0; n < 2; ++n) acc[a][b][m][n] = (f32x4){0.f, 0.f, 0.f, 0.f};
.LBB0_312:
	s_ashr_i32 s95, s94, 31
	s_lshl_b64 s[4:5], s[94:95], 19
	s_add_u32 s6, s68, s4
	s_addc_u32 s7, s69, s5
	s_and_b64 s[4:5], s[0:1], exec
	s_cselect_b32 s3, s7, s97
	s_cselect_b32 s17, s6, s96
	s_ashr_i32 s93, s92, 31
	s_lshl_b64 s[4:5], s[92:93], 19
	s_add_u32 s4, s64, s4
	s_addc_u32 s5, s65, s5
	s_and_b64 s[20:21], s[0:1], exec
	s_cselect_b32 s62, s5, s11
	s_cselect_b32 s93, s4, s10
	s_add_u32 s95, s10, 0x100
	s_addc_u32 s20, s11, 0
	s_add_u32 vcc_lo, s96, 0x40080
	v_mov_b32_e32 v0, 0
	s_addc_u32 vcc_hi, s97, 0
	s_mov_b32 s21, -2
	v_mov_b32_e32 v1, v0
	v_mov_b64_e32 v[2:3], 0
	v_mov_b64_e32 v[4:5], 0
	v_mov_b64_e32 v[6:7], 0
	v_mov_b64_e32 v[16:17], 0
	v_mov_b64_e32 v[18:19], 0
	v_mov_b64_e32 v[20:21], 0
	v_mov_b64_e32 v[22:23], 0
	v_mov_b64_e32 v[32:33], 0
	v_mov_b64_e32 v[34:35], 0
	v_mov_b64_e32 v[36:37], 0
	v_mov_b64_e32 v[38:39], 0
	v_mov_b64_e32 v[48:49], 0
	v_mov_b64_e32 v[50:51], 0
	v_mov_b64_e32 v[52:53], 0
	v_mov_b64_e32 v[54:55], 0
	v_mov_b64_e32 v[8:9], 0
	v_mov_b64_e32 v[10:11], 0
	v_mov_b64_e32 v[12:13], 0
	v_mov_b64_e32 v[14:15], 0
	v_mov_b64_e32 v[24:25], 0
	v_mov_b64_e32 v[26:27], 0
	v_mov_b64_e32 v[28:29], 0
	v_mov_b64_e32 v[30:31], 0
	v_mov_b64_e32 v[40:41], 0
	v_mov_b64_e32 v[42:43], 0
	v_mov_b64_e32 v[44:45], 0
	v_mov_b64_e32 v[46:47], 0
	v_mov_b64_e32 v[56:57], 0
	v_mov_b64_e32 v[58:59], 0
	v_mov_b64_e32 v[60:61], 0
	v_mov_b64_e32 v[62:63], 0
	v_mov_b64_e32 v[66:67], 0
	v_mov_b64_e32 v[68:69], 0
	v_mov_b64_e32 v[70:71], 0
	v_mov_b64_e32 v[72:73], 0
	v_mov_b64_e32 v[82:83], 0
	v_mov_b64_e32 v[84:85], 0
	v_mov_b64_e32 v[86:87], 0
	v_mov_b64_e32 v[88:89], 0
	v_mov_b64_e32 v[98:99], 0
	v_mov_b64_e32 v[100:101], 0
	v_mov_b64_e32 v[102:103], 0
	v_mov_b64_e32 v[104:105], 0
	v_mov_b64_e32 v[114:115], 0
	v_mov_b64_e32 v[116:117], 0
	v_mov_b64_e32 v[118:119], 0
	v_mov_b64_e32 v[120:121], 0
	v_mov_b64_e32 v[74:75], 0
	v_mov_b64_e32 v[76:77], 0
	v_mov_b64_e32 v[78:79], 0
	v_mov_b64_e32 v[80:81], 0
	v_mov_b64_e32 v[90:91], 0
	v_mov_b64_e32 v[92:93], 0
	v_mov_b64_e32 v[94:95], 0
	v_mov_b64_e32 v[96:97], 0
	v_mov_b64_e32 v[106:107], 0
	v_mov_b64_e32 v[108:109], 0
	v_mov_b64_e32 v[110:111], 0
	v_mov_b64_e32 v[112:113], 0
	v_mov_b64_e32 v[122:123], 0
	v_mov_b64_e32 v[124:125], 0
	v_mov_b64_e32 v[126:127], 0
	v_mov_b64_e32 v[128:129], 0

; template <class Epi, bool SP2, class Sched>
; __device__ __forceinline__ void gemm_phase(LAS unsigned char* lds, const Gemm g, const Sched& S, const Epi& E) {
;     ...
;         const bool has_next = S.next(ui + 1, nxt);
;         const char* nA = has_next ? (const char*)g.A + (size_t)nxt.pm * tstep + nxt.ko : cA; const char* nB = has_next ? (const char*)g.Bt + (size_t)nxt.pn * tstepB + nxt.ko : cB;
;     ...
; #pragma unroll
;         for (int a = 0; a < 2; ++a)
; #pragma unroll
;             for (int b = 0; b < 2; ++b)
; #pragma unroll
;                 for (int m = 0; m < 4; ++m)
; #pragma unroll
;                     for (int n = 0; n < 2; ++n) acc[a][b][m][n] = (f32x4){0.f, 0.f, 0.f, 0.f};
.LBB0_380:
	s_ashr_i32 s85, s84, 31
	s_lshl_b64 s[6:7], s[84:85], 19
	s_add_u32 s86, s13, s6
	s_addc_u32 s87, s14, s7
	s_and_b64 s[6:7], s[0:1], exec
	s_cselect_b32 s74, s87, s93
	s_cselect_b32 s75, s86, s92
	s_ashr_i32 s61, s60, 31
	s_lshl_b64 s[6:7], s[60:61], 19
	s_add_u32 s88, s15, s6
	s_addc_u32 s89, s18, s7
	s_and_b64 s[6:7], s[0:1], exec
	s_cselect_b32 s61, s89, s91
	s_cselect_b32 s76, s88, s90
	s_add_u32 s77, s90, 0x100
	s_addc_u32 s20, s91, 0
	s_add_u32 s90, s92, 0x40080
	v_mov_b32_e32 v0, 0
	s_addc_u32 s91, s93, 0
	s_mov_b32 s21, -2
	v_mov_b32_e32 v1, v0
	v_mov_b64_e32 v[2:3], 0
	v_mov_b64_e32 v[4:5], 0
	v_mov_b64_e32 v[6:7], 0
	v_mov_b64_e32 v[12:13], 0
	v_mov_b64_e32 v[14:15], 0
	v_mov_b64_e32 v[20:21], 0
	v_mov_b64_e32 v[22:23], 0
	v_mov_b64_e32 v[28:29], 0
	v_mov_b64_e32 v[30:31], 0
	v_mov_b64_e32 v[36:37], 0
	v_mov_b64_e32 v[38:39], 0
	v_mov_b64_e32 v[44:45], 0
	v_mov_b64_e32 v[46:47], 0
	v_mov_b64_e32 v[52:53], 0
	v_mov_b64_e32 v[54:55], 0
	v_mov_b64_e32 v[8:9], 0
	v_mov_b64_e32 v[10:11], 0
	v_mov_b64_e32 v[16:17], 0
	v_mov_b64_e32 v[18:19], 0
	v_mov_b64_e32 v[24:25], 0
	v_mov_b64_e32 v[26:27], 0
	v_mov_b64_e32 v[32:33], 0
	v_mov_b64_e32 v[34:35], 0
	v_mov_b64_e32 v[40:41], 0
	v_mov_b64_e32 v[42:43], 0
	v_mov_b64_e32 v[48:49], 0
	v_mov_b64_e32 v[50:51], 0
	v_mov_b64_e32 v[56:57], 0
	v_mov_b64_e32 v[58:59], 0
	v_mov_b64_e32 v[60:61], 0
	v_mov_b64_e32 v[62:63], 0
	v_mov_b64_e32 v[66:67], 0
	v_mov_b64_e32 v[68:69], 0
	v_mov_b64_e32 v[70:71], 0
	v_mov_b64_e32 v[72:73], 0
	v_mov_b64_e32 v[82:83], 0
	v_mov_b64_e32 v[84:85], 0
	v_mov_b64_e32 v[86:87], 0
	v_mov_b64_e32 v[88:89], 0
	v_mov_b64_e32 v[114:115], 0
	v_mov_b64_e32 v[116:117], 0
	v_mov_b64_e32 v[118:119], 0
	v_mov_b64_e32 v[120:121], 0
	v_mov_b64_e32 v[130:131], 0
	v_mov_b64_e32 v[132:133], 0
	v_mov_b64_e32 v[134:135], 0
	v_mov_b64_e32 v[136:137], 0
	v_mov_b64_e32 v[74:75], 0
	v_mov_b64_e32 v[76:77], 0
	v_mov_b64_e32 v[78:79], 0
	v_mov_b64_e32 v[80:81], 0
	v_mov_b64_e32 v[90:91], 0
	v_mov_b64_e32 v[92:93], 0
	v_mov_b64_e32 v[94:95], 0
	v_mov_b64_e32 v[96:97], 0
	v_mov_b64_e32 v[122:123], 0
	v_mov_b64_e32 v[124:125], 0
	v_mov_b64_e32 v[126:127], 0
	v_mov_b64_e32 v[128:129], 0
	v_mov_b64_e32 v[138:139], 0
	v_mov_b64_e32 v[140:141], 0
	v_mov_b64_e32 v[142:143], 0
	v_mov_b64_e32 v[144:145], 0

; template <class Epi, bool SP2, class Sched>
; __device__ __forceinline__ void gemm_phase(LAS unsigned char* lds, const Gemm g, const Sched& S, const Epi& E) {
;     ...
;         const bool has_next = S.next(ui + 1, nxt);
;         const char* nA = has_next ? (const char*)g.A + (size_t)nxt.pm * tstep + nxt.ko : cA; const char* nB = has_next ? (const char*)g.Bt + (size_t)nxt.pn * tstepB + nxt.ko : cB;
;     ...
; #pragma unroll
;         for (int a = 0; a < 2; ++a)
; #pragma unroll
;             for (int b = 0; b < 2; ++b)
; #pragma unroll
;                 for (int m = 0; m < 4; ++m)
; #pragma unroll
;                     for (int n = 0; n < 2; ++n) acc[a][b][m][n] = (f32x4){0.f, 0.f, 0.f, 0.f};
.LBB0_954:
	s_ashr_i32 s85, s84, 31
	s_lshl_b64 s[20:21], s[84:85], 19
	s_add_u32 s86, s62, s20
	s_addc_u32 s87, s64, s21
	s_and_b64 s[20:21], s[2:3], exec
	s_cselect_b32 s73, s87, s7
	s_cselect_b32 s74, s86, s6
	s_ashr_i32 s5, s4, 31
	s_lshl_b64 s[20:21], s[4:5], 19
	s_add_u32 s88, s65, s20
	s_addc_u32 s89, s68, s21
	s_and_b64 s[20:21], s[2:3], exec
	s_cselect_b32 s5, s89, s11
	s_cselect_b32 s75, s88, s10
	s_add_u32 s76, s10, 0x100
	s_addc_u32 s20, s11, 0
	s_add_u32 s92, s6, 0x40080
	v_mov_b32_e32 v0, 0
	s_addc_u32 s93, s7, 0
	s_mov_b32 s21, -2
	s_waitcnt lgkmcnt(0)
	v_mov_b32_e32 v1, v0
	v_mov_b64_e32 v[2:3], 0
	v_mov_b64_e32 v[4:5], 0
	v_mov_b64_e32 v[6:7], 0
	v_mov_b64_e32 v[16:17], 0
	v_mov_b64_e32 v[18:19], 0
	v_mov_b64_e32 v[20:21], 0
	v_mov_b64_e32 v[22:23], 0
	v_mov_b64_e32 v[32:33], 0
	v_mov_b64_e32 v[34:35], 0
	v_mov_b64_e32 v[36:37], 0
	v_mov_b64_e32 v[38:39], 0
	v_mov_b64_e32 v[48:49], 0
	v_mov_b64_e32 v[50:51], 0
	v_mov_b64_e32 v[52:53], 0
	v_mov_b64_e32 v[54:55], 0
	v_mov_b64_e32 v[8:9], 0
	v_mov_b64_e32 v[10:11], 0
	v_mov_b64_e32 v[12:13], 0
	v_mov_b64_e32 v[14:15], 0
	v_mov_b64_e32 v[24:25], 0
	v_mov_b64_e32 v[26:27], 0
	v_mov_b64_e32 v[28:29], 0
	v_mov_b64_e32 v[30:31], 0
	v_mov_b64_e32 v[40:41], 0
	v_mov_b64_e32 v[42:43], 0
	v_mov_b64_e32 v[44:45], 0
	v_mov_b64_e32 v[46:47], 0
	v_mov_b64_e32 v[56:57], 0
	v_mov_b64_e32 v[58:59], 0
	v_mov_b64_e32 v[60:61], 0
	v_mov_b64_e32 v[62:63], 0
	v_mov_b64_e32 v[66:67], 0
	v_mov_b64_e32 v[68:69], 0
	v_mov_b64_e32 v[70:71], 0
	v_mov_b64_e32 v[72:73], 0
	v_mov_b64_e32 v[82:83], 0
	v_mov_b64_e32 v[84:85], 0
	v_mov_b64_e32 v[86:87], 0
	v_mov_b64_e32 v[88:89], 0
	v_mov_b64_e32 v[98:99], 0
	v_mov_b64_e32 v[100:101], 0
	v_mov_b64_e32 v[102:103], 0
	v_mov_b64_e32 v[104:105], 0
	v_mov_b64_e32 v[114:115], 0
	v_mov_b64_e32 v[116:117], 0
	v_mov_b64_e32 v[118:119], 0
	v_mov_b64_e32 v[120:121], 0
	v_mov_b64_e32 v[74:75], 0
	v_mov_b64_e32 v[76:77], 0
	v_mov_b64_e32 v[78:79], 0
	v_mov_b64_e32 v[80:81], 0
	v_mov_b64_e32 v[90:91], 0
	v_mov_b64_e32 v[92:93], 0
	v_mov_b64_e32 v[94:95], 0
	v_mov_b64_e32 v[96:97], 0
	v_mov_b64_e32 v[106:107], 0
	v_mov_b64_e32 v[108:109], 0
	v_mov_b64_e32 v[110:111], 0
	v_mov_b64_e32 v[112:113], 0
	v_mov_b64_e32 v[122:123], 0
	v_mov_b64_e32 v[124:125], 0
	v_mov_b64_e32 v[126:127], 0
	v_mov_b64_e32 v[128:129], 0

; template <class Epi, bool SP2, class Sched>
; __device__ __forceinline__ void gemm_phase(LAS unsigned char* lds, const Gemm g, const Sched& S, const Epi& E) {
;     ...
;         const bool has_next = S.next(ui + 1, nxt);
;         const char* nA = has_next ? (const char*)g.A + (size_t)nxt.pm * tstep + nxt.ko : cA; const char* nB = has_next ? (const char*)g.Bt + (size_t)nxt.pn * tstepB + nxt.ko : cB;
;     ...
; #pragma unroll
;         for (int a = 0; a < 2; ++a)
; #pragma unroll
;             for (int b = 0; b < 2; ++b)
; #pragma unroll
;                 for (int m = 0; m < 4; ++m)
; #pragma unroll
;                     for (int n = 0; n < 2; ++n) acc[a][b][m][n] = (f32x4){0.f, 0.f, 0.f, 0.f};
.LBB0_1038:
	s_ashr_i32 s85, s84, 31
	s_lshl_b64 s[6:7], s[84:85], 19
	s_add_u32 s86, s65, s6
	s_addc_u32 s87, s68, s7
	s_and_b64 s[6:7], s[0:1], exec
	s_cselect_b32 s8, s87, s17
	s_cselect_b32 s9, s86, s16
	s_ashr_i32 s61, s60, 31
	s_lshl_b64 s[6:7], s[60:61], 19
	s_add_u32 s88, s69, s6
	s_addc_u32 s89, s72, s7
	s_and_b64 s[6:7], s[0:1], exec
	s_cselect_b32 s12, s89, s11
	s_cselect_b32 s13, s88, s10
	s_add_u32 s14, s10, 0x100
	s_addc_u32 s15, s11, 0
	s_add_u32 s16, s16, 0x40080
	v_mov_b32_e32 v0, 0
	s_addc_u32 s17, s17, 0
	s_mov_b32 s18, -2
	v_mov_b32_e32 v1, v0
	v_mov_b64_e32 v[2:3], 0
	v_mov_b64_e32 v[4:5], 0
	v_mov_b64_e32 v[6:7], 0
	v_mov_b64_e32 v[16:17], 0
	v_mov_b64_e32 v[18:19], 0
	v_mov_b64_e32 v[20:21], 0
	v_mov_b64_e32 v[22:23], 0
	v_mov_b64_e32 v[32:33], 0
	v_mov_b64_e32 v[34:35], 0
	v_mov_b64_e32 v[36:37], 0
	v_mov_b64_e32 v[38:39], 0
	v_mov_b64_e32 v[48:49], 0
	v_mov_b64_e32 v[50:51], 0
	v_mov_b64_e32 v[52:53], 0
	v_mov_b64_e32 v[54:55], 0
	v_mov_b64_e32 v[8:9], 0
	v_mov_b64_e32 v[10:11], 0
	v_mov_b64_e32 v[12:13], 0
	v_mov_b64_e32 v[14:15], 0
	v_mov_b64_e32 v[24:25], 0
	v_mov_b64_e32 v[26:27], 0
	v_mov_b64_e32 v[28:29], 0
	v_mov_b64_e32 v[30:31], 0
	v_mov_b64_e32 v[40:41], 0
	v_mov_b64_e32 v[42:43], 0
	v_mov_b64_e32 v[44:45], 0
	v_mov_b64_e32 v[46:47], 0
	v_mov_b64_e32 v[56:57], 0
	v_mov_b64_e32 v[58:59], 0
	v_mov_b64_e32 v[60:61], 0
	v_mov_b64_e32 v[62:63], 0
	v_mov_b64_e32 v[66:67], 0
	v_mov_b64_e32 v[68:69], 0
	v_mov_b64_e32 v[70:71], 0
	v_mov_b64_e32 v[72:73], 0
	v_mov_b64_e32 v[82:83], 0
	v_mov_b64_e32 v[84:85], 0
	v_mov_b64_e32 v[86:87], 0
	v_mov_b64_e32 v[88:89], 0
	v_mov_b64_e32 v[98:99], 0
	v_mov_b64_e32 v[100:101], 0
	v_mov_b64_e32 v[102:103], 0
	v_mov_b64_e32 v[104:105], 0
	v_mov_b64_e32 v[114:115], 0
	v_mov_b64_e32 v[116:117], 0
	v_mov_b64_e32 v[118:119], 0
	v_mov_b64_e32 v[120:121], 0
	v_mov_b64_e32 v[74:75], 0
	v_mov_b64_e32 v[76:77], 0
	v_mov_b64_e32 v[78:79], 0
	v_mov_b64_e32 v[80:81], 0
	v_mov_b64_e32 v[90:91], 0
	v_mov_b64_e32 v[92:93], 0
	v_mov_b64_e32 v[94:95], 0
	v_mov_b64_e32 v[96:97], 0
	v_mov_b64_e32 v[106:107], 0
	v_mov_b64_e32 v[108:109], 0
	v_mov_b64_e32 v[110:111], 0
	v_mov_b64_e32 v[112:113], 0
	v_mov_b64_e32 v[122:123], 0
	v_mov_b64_e32 v[124:125], 0
	v_mov_b64_e32 v[126:127], 0
	v_mov_b64_e32 v[128:129], 0

; template <class Epi, bool SP2, class Sched>
; __device__ __forceinline__ void gemm_phase(LAS unsigned char* lds, const Gemm g, const Sched& S, const Epi& E) {
;     ...
;         const bool has_next = S.next(ui + 1, nxt);
;         const char* nA = has_next ? (const char*)g.A + (size_t)nxt.pm * tstep + nxt.ko : cA; const char* nB = has_next ? (const char*)g.Bt + (size_t)nxt.pn * tstepB + nxt.ko : cB;
;     ...
; #pragma unroll
;         for (int a = 0; a < 2; ++a)
; #pragma unroll
;             for (int b = 0; b < 2; ++b)
; #pragma unroll
;                 for (int m = 0; m < 4; ++m)
; #pragma unroll
;                     for (int n = 0; n < 2; ++n) acc[a][b][m][n] = (f32x4){0.f, 0.f, 0.f, 0.f};
.LBB0_1117:
	s_ashr_i32 s85, s84, 31
	s_lshl_b64 s[6:7], s[84:85], 21
	s_add_u32 s86, s62, s6
	s_addc_u32 s87, s64, s7
	s_and_b64 s[6:7], s[2:3], exec
	s_cselect_b32 s73, s87, s93
	s_cselect_b32 s74, s86, s92
	s_ashr_i32 s5, s4, 31
	s_lshl_b64 s[6:7], s[4:5], 21
	s_add_u32 s88, s65, s6
	s_addc_u32 s89, s68, s7
	s_and_b64 s[6:7], s[2:3], exec
	s_cselect_b32 s5, s89, s11
	s_cselect_b32 s75, s88, s10
	s_add_u32 s76, s10, 0x100
	s_addc_u32 s20, s11, 0
	s_add_u32 s92, s92, 0x100080
	v_mov_b32_e32 v0, 0
	s_addc_u32 s93, s93, 0
	s_mov_b32 s21, -2
	s_waitcnt lgkmcnt(0)
	v_mov_b32_e32 v1, v0
	v_mov_b64_e32 v[2:3], 0
	v_mov_b64_e32 v[4:5], 0
	v_mov_b64_e32 v[6:7], 0
	v_mov_b64_e32 v[16:17], 0
	v_mov_b64_e32 v[18:19], 0
	v_mov_b64_e32 v[20:21], 0
	v_mov_b64_e32 v[22:23], 0
	v_mov_b64_e32 v[32:33], 0
	v_mov_b64_e32 v[34:35], 0
	v_mov_b64_e32 v[36:37], 0
	v_mov_b64_e32 v[38:39], 0
	v_mov_b64_e32 v[48:49], 0
	v_mov_b64_e32 v[50:51], 0
	v_mov_b64_e32 v[52:53], 0
	v_mov_b64_e32 v[54:55], 0
	v_mov_b64_e32 v[8:9], 0
	v_mov_b64_e32 v[10:11], 0
	v_mov_b64_e32 v[12:13], 0
	v_mov_b64_e32 v[14:15], 0
	v_mov_b64_e32 v[24:25], 0
	v_mov_b64_e32 v[26:27], 0
	v_mov_b64_e32 v[28:29], 0
	v_mov_b64_e32 v[30:31], 0
	v_mov_b64_e32 v[40:41], 0
	v_mov_b64_e32 v[42:43], 0
	v_mov_b64_e32 v[44:45], 0
	v_mov_b64_e32 v[46:47], 0
	v_mov_b64_e32 v[56:57], 0
	v_mov_b64_e32 v[58:59], 0
	v_mov_b64_e32 v[60:61], 0
	v_mov_b64_e32 v[62:63], 0
	v_mov_b64_e32 v[66:67], 0
	v_mov_b64_e32 v[68:69], 0
	v_mov_b64_e32 v[70:71], 0
	v_mov_b64_e32 v[72:73], 0
	v_mov_b64_e32 v[82:83], 0
	v_mov_b64_e32 v[84:85], 0
	v_mov_b64_e32 v[86:87], 0
	v_mov_b64_e32 v[88:89], 0
	v_mov_b64_e32 v[98:99], 0
	v_mov_b64_e32 v[100:101], 0
	v_mov_b64_e32 v[102:103], 0
	v_mov_b64_e32 v[104:105], 0
	v_mov_b64_e32 v[114:115], 0
	v_mov_b64_e32 v[116:117], 0
	v_mov_b64_e32 v[118:119], 0
	v_mov_b64_e32 v[120:121], 0
	v_mov_b64_e32 v[74:75], 0
	v_mov_b64_e32 v[76:77], 0
	v_mov_b64_e32 v[78:79], 0
	v_mov_b64_e32 v[80:81], 0
	v_mov_b64_e32 v[90:91], 0
	v_mov_b64_e32 v[92:93], 0
	v_mov_b64_e32 v[94:95], 0
	v_mov_b64_e32 v[96:97], 0
	v_mov_b64_e32 v[106:107], 0
	v_mov_b64_e32 v[108:109], 0
	v_mov_b64_e32 v[110:111], 0
	v_mov_b64_e32 v[112:113], 0
	v_mov_b64_e32 v[122:123], 0
	v_mov_b64_e32 v[124:125], 0
	v_mov_b64_e32 v[126:127], 0
	v_mov_b64_e32 v[128:129], 0

; template <class Epi, bool SP2, class Sched>
; __device__ __forceinline__ void gemm_phase(LAS unsigned char* lds, const Gemm g, const Sched& S, const Epi& E) {
;     ...
;         const bool has_next = S.next(ui + 1, nxt);
;         const char* nA = has_next ? (const char*)g.A + (size_t)nxt.pm * tstep + nxt.ko : cA; const char* nB = has_next ? (const char*)g.Bt + (size_t)nxt.pn * tstepB + nxt.ko : cB;
;     ...
; #pragma unroll
;         for (int a = 0; a < 2; ++a)
; #pragma unroll
;             for (int b = 0; b < 2; ++b)
; #pragma unroll
;                 for (int m = 0; m < 4; ++m)
; #pragma unroll
;                     for (int n = 0; n < 2; ++n) acc[a][b][m][n] = (f32x4){0.f, 0.f, 0.f, 0.f};
.LBB0_1149:
	s_ashr_i32 s57, s56, 31
	s_lshl_b64 s[20:21], s[56:57], 21
	s_add_u32 s3, s12, s20
	s_addc_u32 s20, s13, s21
	s_ashr_i32 s22, s76, 31
	s_add_u32 s60, s3, s76
	s_addc_u32 s61, s20, s22
	s_and_b64 s[20:21], s[58:59], exec
	s_cselect_b32 s3, s61, s7
	s_cselect_b32 s57, s60, s6
	s_ashr_i32 s53, s52, 31
	s_lshl_b64 s[20:21], s[52:53], 21
	s_add_u32 s20, s14, s20
	s_addc_u32 s21, s15, s21
	s_add_u32 s84, s20, s76
	s_addc_u32 s85, s21, s22
	s_and_b64 s[20:21], s[58:59], exec
	s_cselect_b32 s53, s85, s11
	s_cselect_b32 s77, s84, s10
	s_add_u32 s79, s10, 0x100
	s_addc_u32 s20, s11, 0
	s_add_u32 s86, s6, 0x100080
	v_mov_b32_e32 v0, 0
	s_addc_u32 s87, s7, 0
	s_mov_b32 s21, -2
	v_mov_b32_e32 v1, v0
	v_mov_b64_e32 v[2:3], 0
	v_mov_b64_e32 v[4:5], 0
	v_mov_b64_e32 v[6:7], 0
	v_mov_b64_e32 v[8:9], 0
	v_mov_b64_e32 v[10:11], 0
	v_mov_b64_e32 v[12:13], 0
	v_mov_b64_e32 v[14:15], 0
	v_mov_b64_e32 v[24:25], 0
	v_mov_b64_e32 v[26:27], 0
	v_mov_b64_e32 v[28:29], 0
	v_mov_b64_e32 v[30:31], 0
	v_mov_b64_e32 v[40:41], 0
	v_mov_b64_e32 v[42:43], 0
	v_mov_b64_e32 v[44:45], 0
	v_mov_b64_e32 v[46:47], 0
	v_mov_b64_e32 v[16:17], 0
	v_mov_b64_e32 v[18:19], 0
	v_mov_b64_e32 v[20:21], 0
	v_mov_b64_e32 v[22:23], 0
	v_mov_b64_e32 v[32:33], 0
	v_mov_b64_e32 v[34:35], 0
	v_mov_b64_e32 v[36:37], 0
	v_mov_b64_e32 v[38:39], 0
	v_mov_b64_e32 v[48:49], 0
	v_mov_b64_e32 v[50:51], 0
	v_mov_b64_e32 v[52:53], 0
	v_mov_b64_e32 v[54:55], 0
	v_mov_b64_e32 v[56:57], 0
	v_mov_b64_e32 v[58:59], 0
	v_mov_b64_e32 v[60:61], 0
	v_mov_b64_e32 v[62:63], 0
	v_mov_b64_e32 v[66:67], 0
	v_mov_b64_e32 v[68:69], 0
	v_mov_b64_e32 v[70:71], 0
	v_mov_b64_e32 v[72:73], 0
	v_mov_b64_e32 v[74:75], 0
	v_mov_b64_e32 v[76:77], 0
	v_mov_b64_e32 v[78:79], 0
	v_mov_b64_e32 v[80:81], 0
	v_mov_b64_e32 v[86:87], 0
	v_mov_b64_e32 v[88:89], 0
	v_mov_b64_e32 v[94:95], 0
	v_mov_b64_e32 v[96:97], 0
	v_mov_b64_e32 v[102:103], 0
	v_mov_b64_e32 v[104:105], 0
	v_mov_b64_e32 v[110:111], 0
	v_mov_b64_e32 v[112:113], 0
	v_mov_b64_e32 v[82:83], 0
	v_mov_b64_e32 v[84:85], 0
	v_mov_b64_e32 v[90:91], 0
	v_mov_b64_e32 v[92:93], 0
	v_mov_b64_e32 v[98:99], 0
	v_mov_b64_e32 v[100:101], 0
	v_mov_b64_e32 v[106:107], 0
	v_mov_b64_e32 v[108:109], 0
	v_mov_b64_e32 v[114:115], 0
	v_mov_b64_e32 v[116:117], 0
	v_mov_b64_e32 v[118:119], 0
	v_mov_b64_e32 v[120:121], 0
	v_mov_b64_e32 v[122:123], 0
	v_mov_b64_e32 v[124:125], 0
	v_mov_b64_e32 v[126:127], 0
	v_mov_b64_e32 v[128:129], 0
